# balance K and V^T prologue GEMMs: V^T phase uses bid^128 so every WG runs 3 units instead of 4 or 2
# speedup vs baseline: 1.0012x; 1.0012x over previous
; #define LAS __attribute__((address_space(3)))
; __global__ __launch_bounds__(512, 2) void mega(Params p) {
;     ...
;     for (int pc = 0; pc < total; ++pc) {
;         int z0; asm volatile("s_mov_b32 %0, 0" : "=s"(z0));
;         const int bid = blockIdx.x + z0, nblk = gridDim.x + z0;
;         int kind, arg, chunk;
;         if (pc < 3) { kind = pc == 0 ? K_PROLOGUE : K_GEMM; arg = 17 + pc; chunk = 0; }
;         else { const int q = pc - 3; chunk = q / NSTEP; const int s = q - chunk * NSTEP; kind = p.kind[s]; arg = p.arg[s]; }
;         const int local_seam = arg >> 7; arg &= 0x7f;
;         if (kind == K_GEMM) {
;             if (arg == 1 && pc >= 3) dft_row1024_job(bid, nblk, (const bf16_t*)(p.R1 + z0), p.wp[WP_R0 + z0], p.CB + z0);
;             gemm_phase(bid, nblk, (LAS unsigned char*)shm, arg, chunk, p);
.LBB0_20:
	v_writelane_b32 v254, s5, 28
	s_add_i32 s2, s62, s75
	s_cmp_eq_u32 s5, 2
	s_cselect_b32 s98, 0x80, 0
	s_cmp_eq_u32 s89, 0x100
	s_cselect_b32 s98, s98, 0
	s_xor_b32 s2, s2, s98
	v_writelane_b32 v254, s2, 29
	s_add_i32 s44, s62, s89
	s_and_b32 s49, s48, 0x7f
	v_writelane_b32 v254, s3, 30
	s_cmp_lg_u32 s4, 0
	s_cbranch_scc0 .LBB0_58
	v_readlane_b32 s2, v254, 11
	s_add_i32 s24, s2, s62
	s_ashr_i32 s25, s24, 31
	s_lshl_b64 s[20:21], s[24:25], 11
	s_mul_i32 s2, s20, s29
	s_mul_hi_u32 s3, s20, s28
	s_add_i32 s5, s3, s2
	s_lshr_b64 s[2:3], s[24:25], 21
	s_mul_i32 s2, s2, s28
	s_ashr_i32 s63, s62, 31
	s_add_i32 s23, s5, s2
	s_lshl_b64 s[2:3], s[62:63], 3
	v_readlane_b32 s6, v254, 0
	v_readlane_b32 s7, v254, 1
	s_add_u32 s26, s6, s2
	s_addc_u32 s27, s7, s3
	s_sext_i32_i16 s41, s4
	s_mul_i32 s22, s20, s28
	s_cmp_lt_i32 s41, 7
	s_mov_b64 s[2:3], -1
	s_cbranch_scc1 .LBB0_235
	s_waitcnt lgkmcnt(0)
	v_readlane_b32 s8, v254, 18
	v_readlane_b32 s9, v254, 19
	s_add_u32 s46, s8, s62
	s_addc_u32 s47, s9, s63
	s_cmp_lt_i32 s41, 10
	v_readlane_b32 s10, v254, 20
	v_readlane_b32 s11, v254, 21
	v_readlane_b32 s12, v254, 22
	v_readlane_b32 s13, v254, 23
	v_readlane_b32 s14, v254, 24
	v_readlane_b32 s15, v254, 25
	s_cbranch_scc1 .LBB0_61
	s_cmp_lt_i32 s41, 11
	s_cbranch_scc1 .LBB0_50
	s_cmp_lt_i32 s41, 12
	s_cbranch_scc1 .LBB0_31
	s_and_b32 s2, 0xffff, s4
	s_cmp_eq_u32 s2, 12
	s_cbranch_scc0 .LBB0_30
	v_mov_b32_e32 v0, v169
	v_readlane_b32 s2, v254, 29
	v_readlane_b32 s3, v254, 30
	v_ashrrev_i32_e32 v22, 6, v0
	s_ashr_i32 s3, s2, 31
	v_ashrrev_i32_e32 v23, 31, v22
	v_writelane_b32 v254, s2, 29
	v_mov_b32_e32 v20, v169
	s_nop 0
	v_lshl_add_u64 v[8:9], s[2:3], 3, v[22:23]
	v_writelane_b32 v254, s3, 30
	v_cmp_gt_i64_e32 vcc, s[20:21], v[8:9]
	s_and_saveexec_b64 s[2:3], vcc
	s_cbranch_execz .LBB0_29
	s_load_dwordx2 s[4:5], s[26:27], 0xd0
	v_lshlrev_b32_e32 v0, 5, v20
	v_and_b32_e32 v10, 0x7e0, v0
	v_cmp_lt_i32_e32 vcc, v230, v219
	v_readlane_b32 s12, v254, 29
	s_waitcnt lgkmcnt(0)
	global_load_dwordx4 v[0:3], v10, s[4:5] offset:2064
	global_load_dwordx4 v[4:7], v10, s[4:5] offset:2048
	global_load_dwordx4 v[12:15], v10, s[4:5] offset:16
	global_load_dwordx4 v[16:19], v10, s[4:5]
	v_cndmask_b32_e32 v10, v213, v230, vcc
	v_cmp_lt_i32_e32 vcc, v215, v219
	v_readlane_b32 s13, v254, 30
	s_ashr_i32 s45, s44, 31
	v_cndmask_b32_e32 v21, v213, v215, vcc
	v_cmp_lt_i32_e32 vcc, v121, v219
	v_lshlrev_b32_e32 v24, 2, v21
	s_lshl_b64 s[6:7], s[12:13], 14
	v_cndmask_b32_e32 v21, v213, v121, vcc
	v_cmp_lt_i32_e32 vcc, v122, v219
	v_lshlrev_b64 v[30:31], 11, v[22:23]
	s_lshl_b64 s[8:9], s[22:23], 12
	v_lshlrev_b32_e32 v25, 2, v21
	v_cndmask_b32_e32 v21, v213, v122, vcc
	v_cmp_lt_i32_e32 vcc, v123, v219
	s_lshl_b64 s[4:5], s[44:45], 3
	v_lshl_add_u64 v[30:31], s[6:7], 0, v[30:31]
	s_lshl_b64 s[6:7], s[62:63], 1
	v_readlane_b32 s10, v254, 4
	v_lshlrev_b32_e32 v26, 2, v21
	v_cndmask_b32_e32 v21, v213, v123, vcc
	v_cmp_lt_i32_e32 vcc, v126, v219
	v_and_b32_e32 v29, 63, v20
	s_add_u32 s6, s10, s6
	v_readlane_b32 s10, v254, 5
	v_lshlrev_b32_e32 v27, 2, v21
	v_cndmask_b32_e32 v21, v213, v126, vcc
	v_lshl_or_b32 v30, v29, 4, v30
	s_addc_u32 s7, s10, s7
	v_lshlrev_b32_e32 v28, 2, v21
	v_lshl_add_u64 v[20:21], s[6:7], 0, v[30:31]
	s_lshl_b64 s[6:7], s[44:45], 14
	s_lshl_b64 s[10:11], s[12:13], 15
	s_add_u32 s8, s8, s10
	s_addc_u32 s9, s9, s11
	v_lshlrev_b64 v[22:23], 12, v[22:23]
	v_lshl_add_u64 v[22:23], s[8:9], 0, v[22:23]
	s_lshl_b64 s[8:9], s[62:63], 2
	v_readlane_b32 s10, v254, 14
	v_readlane_b32 s11, v254, 15
	s_add_u32 s8, s10, s8
	v_lshl_or_b32 v22, v29, 5, v22
	s_addc_u32 s9, s11, s9
	v_lshlrev_b32_e32 v10, 2, v10
	v_lshl_add_u64 v[22:23], s[8:9], 0, v[22:23]
	s_lshl_b64 s[8:9], s[44:45], 15
	s_mov_b64 s[10:11], 0

; __global__ __launch_bounds__(512, 2) void mega(Params p) {
;     extern __shared__ __attribute__((aligned(16))) unsigned char shm[];
	.amdhsa_kernel _Z4mega6Params
		.amdhsa_group_segment_fixed_size 0
		.amdhsa_private_segment_fixed_size 0
		.amdhsa_kernarg_size 3584
		.amdhsa_user_sgpr_count 2
		.amdhsa_user_sgpr_dispatch_ptr 0
		.amdhsa_user_sgpr_queue_ptr 0
		.amdhsa_user_sgpr_kernarg_segment_ptr 1
		.amdhsa_user_sgpr_dispatch_id 0
		.amdhsa_user_sgpr_kernarg_preload_length 0
		.amdhsa_user_sgpr_kernarg_preload_offset 0
		.amdhsa_user_sgpr_private_segment_size 0
		.amdhsa_uses_dynamic_stack 0
		.amdhsa_enable_private_segment 0
		.amdhsa_system_sgpr_workgroup_id_x 1
		.amdhsa_system_sgpr_workgroup_id_y 0
		.amdhsa_system_sgpr_workgroup_id_z 0
		.amdhsa_system_sgpr_workgroup_info 0
		.amdhsa_system_vgpr_workitem_id 2
		.amdhsa_next_free_vgpr 256
		.amdhsa_next_free_sgpr 100
		.amdhsa_accum_offset 256
		.amdhsa_reserve_vcc 1
		.amdhsa_float_round_mode_32 0
		.amdhsa_float_round_mode_16_64 0
		.amdhsa_float_denorm_mode_32 3
		.amdhsa_float_denorm_mode_16_64 3
		.amdhsa_dx10_clamp 1
		.amdhsa_ieee_mode 1
		.amdhsa_fp16_overflow 0
		.amdhsa_tg_split 0
		.amdhsa_exception_fp_ieee_invalid_op 0
		.amdhsa_exception_fp_denorm_src 0
		.amdhsa_exception_fp_ieee_div_zero 0
		.amdhsa_exception_fp_ieee_overflow 0
		.amdhsa_exception_fp_ieee_underflow 0
		.amdhsa_exception_fp_ieee_inexact 0
		.amdhsa_exception_int_div_zero 0
	.end_amdhsa_kernel

; __global__ __launch_bounds__(512, 2) void mega(Params p) {
;     extern __shared__ __attribute__((aligned(16))) unsigned char shm[];
amdhsa.kernels:
  - .agpr_count:     0
    .args:
      - .offset:         0
        .size:           3328
        .value_kind:     by_value
      - .offset:         3328
        .size:           4
        .value_kind:     hidden_block_count_x
      - .offset:         3332
        .size:           4
        .value_kind:     hidden_block_count_y
      - .offset:         3336
        .size:           4
        .value_kind:     hidden_block_count_z
      - .offset:         3340
        .size:           2
        .value_kind:     hidden_group_size_x
      - .offset:         3342
        .size:           2
        .value_kind:     hidden_group_size_y
      - .offset:         3344
        .size:           2
        .value_kind:     hidden_group_size_z
      - .offset:         3346
        .size:           2
        .value_kind:     hidden_remainder_x
      - .offset:         3348
        .size:           2
        .value_kind:     hidden_remainder_y
      - .offset:         3350
        .size:           2
        .value_kind:     hidden_remainder_z
      - .offset:         3368
        .size:           8
        .value_kind:     hidden_global_offset_x
      - .offset:         3376
        .size:           8
        .value_kind:     hidden_global_offset_y
      - .offset:         3384
        .size:           8
        .value_kind:     hidden_global_offset_z
      - .offset:         3392
        .size:           2
        .value_kind:     hidden_grid_dims
      - .offset:         3416
        .size:           8
        .value_kind:     hidden_multigrid_sync_arg
      - .offset:         3448
        .size:           4
        .value_kind:     hidden_dynamic_lds_size
    .group_segment_fixed_size: 0
    .kernarg_segment_align: 8
    .kernarg_segment_size: 3584
    .language:       OpenCL C
    .language_version:
      - 2
      - 0
    .max_flat_workgroup_size: 512
    .name:           _Z4mega6Params
    .private_segment_fixed_size: 0
    .sgpr_count:     106
    .sgpr_spill_count: 113
    .symbol:         _Z4mega6Params.kd
    .uniform_work_group_size: 1
    .uses_dynamic_stack: false
    .vgpr_count:     256
    .vgpr_spill_count: 0
    .wavefront_size: 64
